# attention: tile staging (LDS writes + global loads) issued inside the QK MFMA shadows instead of after the last MFMA
# speedup vs baseline: 1.0172x; 1.0090x over previous
; __device__ __forceinline__ void qkt(f32x16& p0, f32x16& p1, const unsigned char* Ks, const i32x8* qr, int r32, int hi) {
;   p0 = f32x16{}; p1 = f32x16{};
; #pragma unroll
;   for (int m = 0; m < 3; ++m) { const int cb = m * 64 + hi * 32;
;     const u32x4 a0 = *reinterpret_cast<const u32x4*>(Ks + KSWZ(r32, cb)), a1 = *reinterpret_cast<const u32x4*>(Ks + KSWZ(r32, cb) + 16);
;     const u32x4 c0 = *reinterpret_cast<const u32x4*>(Ks + KSWZ(32 + r32, cb)), c1 = *reinterpret_cast<const u32x4*>(Ks + KSWZ(32 + r32, cb) + 16);
;     const i32x8 b0 = {(int)a0.x, (int)a0.y, (int)a0.z, (int)a0.w, (int)a1.x, (int)a1.y, (int)a1.z, (int)a1.w};
;     const i32x8 b1 = {(int)c0.x, (int)c0.y, (int)c0.z, (int)c0.w, (int)c1.x, (int)c1.y, (int)c1.z, (int)c1.w};
;     p0 = __builtin_amdgcn_mfma_scale_f32_32x32x64_f8f6f4(b0, qr[m], p0, 0, 0, 0, 0x7F7F7F7F, 0, 0x7F7F7F7F);
;     p1 = __builtin_amdgcn_mfma_scale_f32_32x32x64_f8f6f4(b1, qr[m], p1, 0, 0, 0, 0x7F7F7F7F, 0, 0x7F7F7F7F); }
; }
; __device__ __forceinline__ void attn_body(const unsigned char* __restrict__ Qb, const unsigned char* __restrict__ Kh, const unsigned char* __restrict__ Vt,
;                                           bf16_t* __restrict__ Ob, int seq, char* lds) {
;     ...
;   f32x16 pA0, pA1, pB0, pB1; float mnA, mnB, alA, alB; i32x8 pa; const int NT = seq / KVBLK;
.Latt_loop:
	s_setprio 0
	s_and_b32 s0, s6, 3
	s_mul_i32 s0, s0, 13312
	v_add_u32_e32 v229, s0, v220
	s_add_u32 s0, s6, 1
	s_and_b32 s0, s0, 3
	s_mul_i32 s0, s0, 13312
	v_add_u32_e32 v225, s0, v220
	s_cmp_eq_u32 s6, 0
	s_cbranch_scc1 .Latt_m_first
	s_add_u32 s0, s6, 3
	s_and_b32 s0, s0, 3
	s_mul_i32 s0, s0, 10240
	v_add_u32_e32 v224, s0, v221
	s_add_u32 s4, s6, 2
	s_and_b32 s0, s4, 3
	s_mul_i32 s1, s0, 10240
	s_mul_i32 s5, s0, 13312
	ds_read_b128 v[176:179], v224 offset:0
	ds_read_b128 v[180:183], v224 offset:16
	ds_read_b128 v[184:187], v224 offset:2560
	ds_read_b128 v[188:191], v224 offset:2576
	s_waitcnt lgkmcnt(4)
	v_mfma_scale_f32_32x32x64_f8f6f4 v[64:79], v[128:135], v[96:103], v[160:175], v235, v201 op_sel_hi:[0,0,0]
	ds_read_b128 v[128:131], v229 offset:41088
	ds_read_b128 v[132:135], v229 offset:41104
	v_mfma_scale_f32_32x32x64_f8f6f4 v[80:95], v[136:143], v[96:103], v[160:175], v235, v201 op_sel_hi:[0,0,0]
	ds_read_b128 v[136:139], v229 offset:47744
	ds_read_b128 v[140:143], v229 offset:47760
	s_cmp_lt_u32 s4, 128
	s_cbranch_scc0 .Latt_ms_nowr
	v_add_u32_e32 v228, s1, v217
	v_add_u32_e32 v226, s5, v218
	s_waitcnt vmcnt(0)
	ds_write2_b32 v228, v202, v204 offset1:1
	ds_write2_b32 v228, v203, v205 offset0:8 offset1:9
	ds_write_b128 v226, v[206:209] offset:40960
	s_cmp_lt_u32 s12, 4
	s_cbranch_scc0 .Latt_ms_w1
	v_add_u32_e32 v231, s5, v219
	ds_write_b128 v231, v[210:213] offset:40960
.Latt_ms_w1:
.Latt_ms_nowr:
	v_mfma_scale_f32_32x32x64_f8f6f4 v[64:79], v[144:151], v[104:111], v[64:79], v235, v201 op_sel_hi:[0,0,0]
	ds_read_b128 v[144:147], v225 offset:41024
	ds_read_b128 v[148:151], v225 offset:41040
	v_mfma_scale_f32_32x32x64_f8f6f4 v[80:95], v[152:159], v[104:111], v[80:95], v235, v201 op_sel_hi:[0,0,0]
	ds_read_b128 v[152:155], v225 offset:47680
	ds_read_b128 v[156:159], v225 offset:47696
	s_cmp_lt_u32 s4, 127
	s_cbranch_scc0 .Latt_ms_nold
	global_load_dwordx4 v[202:205], v216, s[10:11]
	global_load_dwordx4 v[206:209], v214, s[8:9]
	s_cmp_lt_u32 s12, 4
	s_cbranch_scc0 .Latt_ms_l1
	global_load_dwordx4 v[210:213], v215, s[8:9]

; __device__ __forceinline__ void qkt(f32x16& p0, f32x16& p1, const unsigned char* Ks, const i32x8* qr, int r32, int hi) {
;   p0 = f32x16{}; p1 = f32x16{};
; #pragma unroll
;   for (int m = 0; m < 3; ++m) { const int cb = m * 64 + hi * 32;
;     const u32x4 a0 = *reinterpret_cast<const u32x4*>(Ks + KSWZ(r32, cb)), a1 = *reinterpret_cast<const u32x4*>(Ks + KSWZ(r32, cb) + 16);
;     const u32x4 c0 = *reinterpret_cast<const u32x4*>(Ks + KSWZ(32 + r32, cb)), c1 = *reinterpret_cast<const u32x4*>(Ks + KSWZ(32 + r32, cb) + 16);
;     const i32x8 b0 = {(int)a0.x, (int)a0.y, (int)a0.z, (int)a0.w, (int)a1.x, (int)a1.y, (int)a1.z, (int)a1.w};
;     const i32x8 b1 = {(int)c0.x, (int)c0.y, (int)c0.z, (int)c0.w, (int)c1.x, (int)c1.y, (int)c1.z, (int)c1.w};
;     p0 = __builtin_amdgcn_mfma_scale_f32_32x32x64_f8f6f4(b0, qr[m], p0, 0, 0, 0, 0x7F7F7F7F, 0, 0x7F7F7F7F);
;     p1 = __builtin_amdgcn_mfma_scale_f32_32x32x64_f8f6f4(b1, qr[m], p1, 0, 0, 0, 0x7F7F7F7F, 0, 0x7F7F7F7F); }
; }
; __device__ __forceinline__ void pv_d0(f32x16* o, const unsigned char* Vs, const i32x8& pa, int r32, int hi) {
; #pragma unroll
;   for (int d0 = 0; d0 < 4; ++d0) { const unsigned char* vp = Vs + (32 * d0 + r32) * 80 + hi * 32;
;     const u32x4 a0 = *reinterpret_cast<const u32x4*>(vp), a1 = *reinterpret_cast<const u32x4*>(vp + 16);
;     const i32x8 vb = {(int)a0.x, (int)a0.y, (int)a0.z, (int)a0.w, (int)a1.x, (int)a1.y, (int)a1.z, (int)a1.w};
;     o[d0] = __builtin_amdgcn_mfma_scale_f32_32x32x64_f8f6f4(pa, vb, o[d0], 0, 0, 0, 0x7A7A7A7A, 0, 0x7F7F7F7F); }
; }
.Latt_ms_nold:
	s_waitcnt lgkmcnt(9)
	v_mfma_scale_f32_32x32x64_f8f6f4 v[64:79], v[128:135], v[112:119], v[64:79], v235, v201 op_sel_hi:[0,0,0]
	ds_read_b128 v[128:131], v225 offset:40960
	ds_read_b128 v[132:135], v225 offset:40976
	s_waitcnt lgkmcnt(9)
	v_mfma_scale_f32_32x32x64_f8f6f4 v[80:95], v[136:143], v[112:119], v[80:95], v235, v201 op_sel_hi:[0,0,0]
	ds_read_b128 v[136:139], v225 offset:47616
	ds_read_b128 v[140:143], v225 offset:47632
	s_waitcnt lgkmcnt(8)
	v_mfma_scale_f32_32x32x64_f8f6f4 v[0:15], v[120:127], v[176:183], v[0:15], v237, v235 op_sel_hi:[0,0,0]
	ds_read_b128 v[176:179], v224 offset:5120
	ds_read_b128 v[180:183], v224 offset:5136
	v_mfma_scale_f32_32x32x64_f8f6f4 v[16:31], v[120:127], v[184:191], v[16:31], v237, v235 op_sel_hi:[0,0,0]
	ds_read_b128 v[184:187], v224 offset:7680
	ds_read_b128 v[188:191], v224 offset:7696
	s_waitcnt lgkmcnt(2)
	v_mfma_scale_f32_32x32x64_f8f6f4 v[32:47], v[120:127], v[176:183], v[32:47], v237, v235 op_sel_hi:[0,0,0]
	s_waitcnt lgkmcnt(0)
	v_mfma_scale_f32_32x32x64_f8f6f4 v[48:63], v[120:127], v[184:191], v[48:63], v237, v235 op_sel_hi:[0,0,0]
	s_branch .Latt_m_done
.Latt_m_first:
	s_add_u32 s4, s6, 2
	s_and_b32 s0, s4, 3
	s_mul_i32 s1, s0, 10240
	s_mul_i32 s5, s0, 13312
	s_waitcnt lgkmcnt(0)
	v_mfma_scale_f32_32x32x64_f8f6f4 v[64:79], v[128:135], v[96:103], v[160:175], v235, v201 op_sel_hi:[0,0,0]
	ds_read_b128 v[128:131], v229 offset:41088
	ds_read_b128 v[132:135], v229 offset:41104
	v_mfma_scale_f32_32x32x64_f8f6f4 v[80:95], v[136:143], v[96:103], v[160:175], v235, v201 op_sel_hi:[0,0,0]
	ds_read_b128 v[136:139], v229 offset:47744
	ds_read_b128 v[140:143], v229 offset:47760
	s_cmp_lt_u32 s4, 128
	s_cbranch_scc0 .Latt_mf_nowr
	v_add_u32_e32 v228, s1, v217
	v_add_u32_e32 v226, s5, v218
	s_waitcnt vmcnt(0)
	ds_write2_b32 v228, v202, v204 offset1:1
	ds_write2_b32 v228, v203, v205 offset0:8 offset1:9
	ds_write_b128 v226, v[206:209] offset:40960
	s_cmp_lt_u32 s12, 4
	s_cbranch_scc0 .Latt_mf_w1
	v_add_u32_e32 v231, s5, v219
	ds_write_b128 v231, v[210:213] offset:40960

; __device__ __forceinline__ void qkt(f32x16& p0, f32x16& p1, const unsigned char* Ks, const i32x8* qr, int r32, int hi) {
;   p0 = f32x16{}; p1 = f32x16{};
; #pragma unroll
;   for (int m = 0; m < 3; ++m) { const int cb = m * 64 + hi * 32;
;     const u32x4 a0 = *reinterpret_cast<const u32x4*>(Ks + KSWZ(r32, cb)), a1 = *reinterpret_cast<const u32x4*>(Ks + KSWZ(r32, cb) + 16);
;     const u32x4 c0 = *reinterpret_cast<const u32x4*>(Ks + KSWZ(32 + r32, cb)), c1 = *reinterpret_cast<const u32x4*>(Ks + KSWZ(32 + r32, cb) + 16);
;     const i32x8 b0 = {(int)a0.x, (int)a0.y, (int)a0.z, (int)a0.w, (int)a1.x, (int)a1.y, (int)a1.z, (int)a1.w};
;     const i32x8 b1 = {(int)c0.x, (int)c0.y, (int)c0.z, (int)c0.w, (int)c1.x, (int)c1.y, (int)c1.z, (int)c1.w};
;     p0 = __builtin_amdgcn_mfma_scale_f32_32x32x64_f8f6f4(b0, qr[m], p0, 0, 0, 0, 0x7F7F7F7F, 0, 0x7F7F7F7F);
;     p1 = __builtin_amdgcn_mfma_scale_f32_32x32x64_f8f6f4(b1, qr[m], p1, 0, 0, 0, 0x7F7F7F7F, 0, 0x7F7F7F7F); }
; }
.Latt_mf_nold:
	s_waitcnt lgkmcnt(9)
	v_mfma_scale_f32_32x32x64_f8f6f4 v[64:79], v[128:135], v[112:119], v[64:79], v235, v201 op_sel_hi:[0,0,0]
	ds_read_b128 v[128:131], v225 offset:40960
	ds_read_b128 v[132:135], v225 offset:40976
	s_waitcnt lgkmcnt(9)
	v_mfma_scale_f32_32x32x64_f8f6f4 v[80:95], v[136:143], v[112:119], v[80:95], v235, v201 op_sel_hi:[0,0,0]
	ds_read_b128 v[136:139], v225 offset:47616
	ds_read_b128 v[140:143], v225 offset:47632
	s_nop 15
	s_nop 7
.Latt_m_done:
	s_nop 3
	s_cmp_eq_u32 s7, 0
	s_cbranch_scc1 .Latt_m_nobar
	s_waitcnt lgkmcnt(0)
	s_barrier
